# hyena sample item start-up: twiddle copy and the 16 filter-tap pairs loaded with all loads in flight (were 8 + 16 serialized load->wait->LDS write rounds)
# speedup vs baseline: 1.0652x; 1.0124x over previous
.LBB0_622:
	v_ashrrev_i32_e32 v8, 6, v5
	v_lshl_add_u32 v22, v8, 3, v0
	global_load_dwordx2 v[6:7], v[2:3], off
	v_lshl_add_u64 v[2:3], v[2:3], 0, s[16:17]
	global_load_dwordx2 v[8:9], v[2:3], off
	v_lshl_add_u64 v[2:3], v[2:3], 0, s[16:17]
	global_load_dwordx2 v[10:11], v[2:3], off
	v_lshl_add_u64 v[2:3], v[2:3], 0, s[16:17]
	global_load_dwordx2 v[12:13], v[2:3], off
	v_lshl_add_u64 v[2:3], v[2:3], 0, s[16:17]
	global_load_dwordx2 v[14:15], v[2:3], off
	v_lshl_add_u64 v[2:3], v[2:3], 0, s[16:17]
	global_load_dwordx2 v[16:17], v[2:3], off
	v_lshl_add_u64 v[2:3], v[2:3], 0, s[16:17]
	global_load_dwordx2 v[18:19], v[2:3], off
	v_lshl_add_u64 v[2:3], v[2:3], 0, s[16:17]
	global_load_dwordx2 v[20:21], v[2:3], off
	v_lshl_add_u64 v[2:3], v[2:3], 0, s[16:17]
	s_waitcnt vmcnt(7)
	ds_write_b64 v22, v[6:7]
	s_waitcnt vmcnt(6)
	ds_write_b64 v22, v[8:9] offset:4160
	s_waitcnt vmcnt(5)
	ds_write_b64 v22, v[10:11] offset:8320
	s_waitcnt vmcnt(4)
	ds_write_b64 v22, v[12:13] offset:12480
	s_waitcnt vmcnt(3)
	ds_write_b64 v22, v[14:15] offset:16640
	s_waitcnt vmcnt(2)
	ds_write_b64 v22, v[16:17] offset:20800
	s_waitcnt vmcnt(1)
	ds_write_b64 v22, v[18:19] offset:24960
	s_waitcnt vmcnt(0)
	ds_write_b64 v22, v[20:21] offset:29120
	v_add_u32_e32 v0, 0x8000, v0

.LBB0_635:
	s_or_b64 exec, exec, s[0:1]
	v_add_u32_e32 v52, 0x200, v50
	v_lshl_add_u32 v148, v50, 3, v205
	v_cmp_lt_i32_e32 vcc, s3, v50
	s_mov_b64 s[0:1], -1
	v_mov_b64_e32 v[8:9], s[38:39]
	v_mov_b32_e32 v6, v52
	s_and_saveexec_b64 s[42:43], vcc
	s_cbranch_execz .LBB0_639
	s_movk_i32 s0, 0x1000
	v_cmp_ne_u32_e64 s[0:1], s0, v52
	s_mov_b64 s[44:45], 0
	s_and_saveexec_b64 s[46:47], s[0:1]
	s_mov_b64 s[44:45], exec
	v_sub_u32_e32 v6, 0x1e00, v50
	s_or_b64 exec, exec, s[46:47]
	v_mov_b64_e32 v[8:9], s[20:21]
	s_orn2_b64 s[0:1], s[44:45], exec

.LBB0_647:
	s_or_b64 exec, exec, s[0:1]
	v_add_u32_e32 v54, 0x400, v50
	v_cmp_lt_i32_e32 vcc, s84, v50
	s_mov_b64 s[0:1], -1
	v_mov_b64_e32 v[10:11], s[38:39]
	v_mov_b32_e32 v8, v54
	s_and_saveexec_b64 s[42:43], vcc
	s_cbranch_execz .LBB0_651
	s_movk_i32 s0, 0x1000
	v_cmp_ne_u32_e64 s[0:1], s0, v54
	s_mov_b64 s[44:45], 0
	s_and_saveexec_b64 s[46:47], s[0:1]
	s_mov_b64 s[44:45], exec
	v_sub_u32_e32 v8, 0x1c00, v50
	s_or_b64 exec, exec, s[46:47]
	v_mov_b64_e32 v[10:11], s[20:21]
	s_orn2_b64 s[0:1], s[44:45], exec

.LBB0_659:
	s_or_b64 exec, exec, s[0:1]
	v_add_u32_e32 v56, 0x600, v50
	s_movk_i32 s0, 0x9ff
	v_cmp_lt_i32_e32 vcc, s0, v50
	s_mov_b64 s[0:1], -1
	v_mov_b64_e32 v[12:13], s[38:39]
	v_mov_b32_e32 v10, v56
	s_and_saveexec_b64 s[42:43], vcc
	s_cbranch_execz .LBB0_663
	s_movk_i32 s0, 0x1000
	v_cmp_ne_u32_e64 s[0:1], s0, v56
	s_mov_b64 s[44:45], 0
	s_and_saveexec_b64 s[46:47], s[0:1]
	s_mov_b64 s[44:45], exec
	v_sub_u32_e32 v10, 0x1a00, v50
	s_or_b64 exec, exec, s[46:47]
	v_mov_b64_e32 v[12:13], s[20:21]
	s_orn2_b64 s[0:1], s[44:45], exec

.LBB0_671:
	s_or_b64 exec, exec, s[0:1]
	v_add_u32_e32 v58, 0x800, v50
	s_movk_i32 s0, 0x7ff
	v_cmp_lt_i32_e32 vcc, s0, v50
	s_mov_b64 s[0:1], -1
	v_mov_b64_e32 v[14:15], s[38:39]
	v_mov_b32_e32 v12, v58
	s_and_saveexec_b64 s[42:43], vcc
	s_cbranch_execz .LBB0_675
	s_movk_i32 s0, 0x1000
	v_cmp_ne_u32_e64 s[0:1], s0, v58
	s_mov_b64 s[44:45], 0
	s_and_saveexec_b64 s[46:47], s[0:1]
	s_mov_b64 s[44:45], exec
	v_sub_u32_e32 v12, 0x1800, v50
	s_or_b64 exec, exec, s[46:47]
	v_mov_b64_e32 v[14:15], s[20:21]
	s_orn2_b64 s[0:1], s[44:45], exec

.LBB0_683:
	s_or_b64 exec, exec, s[0:1]
	v_add_u32_e32 v60, 0xa00, v50
	v_cmp_lt_i32_e32 vcc, s22, v50
	s_mov_b64 s[0:1], -1
	v_mov_b64_e32 v[16:17], s[38:39]
	v_mov_b32_e32 v14, v60
	s_and_saveexec_b64 s[42:43], vcc
	s_cbranch_execz .LBB0_687
	s_movk_i32 s0, 0x1000
	v_cmp_ne_u32_e64 s[0:1], s0, v60
	s_mov_b64 s[44:45], 0
	s_and_saveexec_b64 s[46:47], s[0:1]
	s_mov_b64 s[44:45], exec
	v_sub_u32_e32 v14, 0x1600, v50
	s_or_b64 exec, exec, s[46:47]
	v_mov_b64_e32 v[16:17], s[20:21]
	s_orn2_b64 s[0:1], s[44:45], exec

.LBB0_695:
	s_or_b64 exec, exec, s[0:1]
	v_add_u32_e32 v62, 0xc00, v50
	v_cmp_lt_i32_e32 vcc, s71, v50
	s_mov_b64 s[0:1], -1
	v_mov_b64_e32 v[18:19], s[38:39]
	v_mov_b32_e32 v16, v62
	s_and_saveexec_b64 s[42:43], vcc
	s_cbranch_execz .LBB0_699
	s_movk_i32 s0, 0x1000
	v_cmp_ne_u32_e64 s[0:1], s0, v62
	s_mov_b64 s[44:45], 0
	s_and_saveexec_b64 s[46:47], s[0:1]
	s_mov_b64 s[44:45], exec
	v_sub_u32_e32 v16, 0x1400, v50
	s_or_b64 exec, exec, s[46:47]
	v_mov_b64_e32 v[18:19], s[20:21]
	s_orn2_b64 s[0:1], s[44:45], exec

.LBB0_707:
	s_or_b64 exec, exec, s[0:1]
	v_add_u32_e32 v64, 0xe00, v50
	v_cmp_lt_i32_e32 vcc, s29, v50
	s_mov_b64 s[0:1], -1
	v_mov_b64_e32 v[20:21], s[38:39]
	v_mov_b32_e32 v18, v64
	s_and_saveexec_b64 s[42:43], vcc
	s_cbranch_execz .LBB0_711
	s_movk_i32 s0, 0x1000
	v_cmp_ne_u32_e64 s[0:1], s0, v64
	s_mov_b64 s[44:45], 0
	s_and_saveexec_b64 s[46:47], s[0:1]
	s_mov_b64 s[44:45], exec
	v_sub_u32_e32 v18, 0x1200, v50
	s_or_b64 exec, exec, s[46:47]
	v_mov_b64_e32 v[20:21], s[20:21]
	s_orn2_b64 s[0:1], s[44:45], exec

.LBB0_719:
	s_or_b64 exec, exec, s[0:1]
	v_add_u32_e32 v0, 0x1000, v50
	v_cmp_lt_i32_e32 vcc, -1, v50
	s_mov_b64 s[0:1], -1
	v_mov_b64_e32 v[22:23], s[38:39]
	v_mov_b32_e32 v20, v0
	s_and_saveexec_b64 s[42:43], vcc
	s_cbranch_execz .LBB0_723
	v_cmp_ne_u32_e64 s[0:1], 0, v50
	s_mov_b64 s[44:45], 0
	s_and_saveexec_b64 s[46:47], s[0:1]
	s_mov_b64 s[44:45], exec
	v_sub_u32_e32 v20, 0x1000, v50
	s_or_b64 exec, exec, s[46:47]
	v_mov_b64_e32 v[22:23], s[20:21]
	s_orn2_b64 s[0:1], s[44:45], exec

.LBB0_731:
	s_or_b64 exec, exec, s[0:1]
	v_add_u32_e32 v53, 0x1200, v50
	s_movk_i32 s0, 0xfdff
	v_cmp_lt_i32_e32 vcc, s0, v50
	s_mov_b64 s[0:1], -1
	v_mov_b64_e32 v[24:25], s[38:39]
	v_mov_b32_e32 v22, v53
	s_and_saveexec_b64 s[42:43], vcc
	s_cbranch_execz .LBB0_735
	s_movk_i32 s0, 0x1000
	v_cmp_ne_u32_e64 s[0:1], s0, v53
	s_mov_b64 s[44:45], 0
	s_and_saveexec_b64 s[46:47], s[0:1]
	s_mov_b64 s[44:45], exec
	v_sub_u32_e32 v22, 0xe00, v50
	s_or_b64 exec, exec, s[46:47]
	v_mov_b64_e32 v[24:25], s[20:21]
	s_orn2_b64 s[0:1], s[44:45], exec

.LBB0_743:
	s_or_b64 exec, exec, s[0:1]
	v_add_u32_e32 v55, 0x1400, v50
	s_movk_i32 s0, 0xfbff
	v_cmp_lt_i32_e32 vcc, s0, v50
	s_mov_b64 s[0:1], -1
	v_mov_b64_e32 v[26:27], s[38:39]
	v_mov_b32_e32 v24, v55
	s_and_saveexec_b64 s[42:43], vcc
	s_cbranch_execz .LBB0_747
	s_movk_i32 s0, 0x1000
	v_cmp_ne_u32_e64 s[0:1], s0, v55
	s_mov_b64 s[44:45], 0
	s_and_saveexec_b64 s[46:47], s[0:1]
	s_mov_b64 s[44:45], exec
	v_sub_u32_e32 v24, 0xc00, v50
	s_or_b64 exec, exec, s[46:47]
	v_mov_b64_e32 v[26:27], s[20:21]
	s_orn2_b64 s[0:1], s[44:45], exec

.LBB0_755:
	s_or_b64 exec, exec, s[0:1]
	v_add_u32_e32 v57, 0x1600, v50
	s_movk_i32 s0, 0xf9ff
	v_cmp_lt_i32_e32 vcc, s0, v50
	s_mov_b64 s[0:1], -1
	v_mov_b64_e32 v[28:29], s[38:39]
	v_mov_b32_e32 v26, v57
	s_and_saveexec_b64 s[42:43], vcc
	s_cbranch_execz .LBB0_759
	s_movk_i32 s0, 0x1000
	v_cmp_ne_u32_e64 s[0:1], s0, v57
	s_mov_b64 s[44:45], 0
	s_and_saveexec_b64 s[46:47], s[0:1]
	s_mov_b64 s[44:45], exec
	v_sub_u32_e32 v26, 0xa00, v50
	s_or_b64 exec, exec, s[46:47]
	v_mov_b64_e32 v[28:29], s[20:21]
	s_orn2_b64 s[0:1], s[44:45], exec

.LBB0_767:
	s_or_b64 exec, exec, s[0:1]
	v_add_u32_e32 v59, 0x1800, v50
	s_movk_i32 s0, 0xf7ff
	v_cmp_lt_i32_e32 vcc, s0, v50
	s_mov_b64 s[0:1], -1
	v_mov_b64_e32 v[30:31], s[38:39]
	v_mov_b32_e32 v28, v59
	s_and_saveexec_b64 s[42:43], vcc
	s_cbranch_execz .LBB0_771
	s_movk_i32 s0, 0x1000
	v_cmp_ne_u32_e64 s[0:1], s0, v59
	s_mov_b64 s[44:45], 0
	s_and_saveexec_b64 s[46:47], s[0:1]
	s_mov_b64 s[44:45], exec
	v_sub_u32_e32 v28, 0x800, v50
	s_or_b64 exec, exec, s[46:47]
	v_mov_b64_e32 v[30:31], s[20:21]
	s_orn2_b64 s[0:1], s[44:45], exec

.LBB0_779:
	s_or_b64 exec, exec, s[0:1]
	v_add_u32_e32 v61, 0x1a00, v50
	s_movk_i32 s0, 0xf5ff
	v_cmp_lt_i32_e32 vcc, s0, v50
	s_mov_b64 s[0:1], -1
	v_mov_b64_e32 v[32:33], s[38:39]
	v_mov_b32_e32 v30, v61
	s_and_saveexec_b64 s[42:43], vcc
	s_cbranch_execz .LBB0_783
	s_movk_i32 s0, 0x1000
	v_cmp_ne_u32_e64 s[0:1], s0, v61
	s_mov_b64 s[44:45], 0
	s_and_saveexec_b64 s[46:47], s[0:1]
	s_mov_b64 s[44:45], exec
	v_sub_u32_e32 v30, 0x600, v50
	s_or_b64 exec, exec, s[46:47]
	v_mov_b64_e32 v[32:33], s[20:21]
	s_orn2_b64 s[0:1], s[44:45], exec

.LBB0_791:
	s_or_b64 exec, exec, s[0:1]
	v_add_u32_e32 v63, 0x1c00, v50
	s_movk_i32 s0, 0xf3ff
	v_cmp_lt_i32_e32 vcc, s0, v50
	s_mov_b64 s[0:1], -1
	v_mov_b64_e32 v[34:35], s[38:39]
	v_mov_b32_e32 v32, v63
	s_and_saveexec_b64 s[42:43], vcc
	s_cbranch_execz .LBB0_795
	s_movk_i32 s0, 0x1000
	v_cmp_ne_u32_e64 s[0:1], s0, v63
	s_mov_b64 s[44:45], 0
	s_and_saveexec_b64 s[46:47], s[0:1]
	s_mov_b64 s[44:45], exec
	v_sub_u32_e32 v32, 0x400, v50
	s_or_b64 exec, exec, s[46:47]
	v_mov_b64_e32 v[34:35], s[20:21]
	s_orn2_b64 s[0:1], s[44:45], exec

.LBB0_803:
	s_or_b64 exec, exec, s[0:1]
	v_add_u32_e32 v65, 0x1e00, v50
	s_movk_i32 s0, 0xf1ff
	v_cmp_lt_i32_e32 vcc, s0, v50
	s_mov_b64 s[0:1], -1
	v_mov_b64_e32 v[36:37], s[38:39]
	v_mov_b32_e32 v34, v65
	s_and_saveexec_b64 s[38:39], vcc
	s_cbranch_execz .LBB0_807
	s_movk_i32 s0, 0x1000
	v_cmp_ne_u32_e64 s[0:1], s0, v65
	s_mov_b64 s[42:43], 0
	s_and_saveexec_b64 s[44:45], s[0:1]
	s_mov_b64 s[42:43], exec
	v_sub_u32_e32 v34, 0x200, v50
	s_or_b64 exec, exec, s[44:45]
	v_mov_b64_e32 v[36:37], s[20:21]
	s_orn2_b64 s[0:1], s[42:43], exec

.LBB0_815:
	s_or_b64 exec, exec, s[0:1]
	s_waitcnt vmcnt(0)
	ds_write_b64 v148, v[2:3]
	ds_write_b64 v148, v[4:5] offset:4096
	ds_write_b64 v148, v[6:7] offset:8192
	ds_write_b64 v148, v[8:9] offset:12288
	ds_write_b64 v148, v[10:11] offset:16384
	ds_write_b64 v148, v[12:13] offset:20480
	ds_write_b64 v148, v[14:15] offset:24576
	ds_write_b64 v148, v[16:17] offset:28672
	ds_write_b64 v148, v[18:19] offset:32768
	ds_write_b64 v148, v[20:21] offset:36864
	ds_write_b64 v148, v[22:23] offset:40960
	ds_write_b64 v148, v[24:25] offset:45056
	ds_write_b64 v148, v[26:27] offset:49152
	ds_write_b64 v148, v[28:29] offset:53248
	ds_write_b64 v148, v[30:31] offset:57344
	v_add_f32_e64 v2, |v2|, |v4|
	v_add_f32_e64 v2, v2, |v6|
	v_add_f32_e64 v2, v2, |v8|
	v_add_f32_e64 v2, v2, |v10|
	v_add_f32_e64 v2, v2, |v12|
	v_add_f32_e64 v2, v2, |v14|
	v_add_f32_e64 v2, v2, |v16|
	v_add_f32_e64 v2, v2, |v18|
	v_add_f32_e64 v2, v2, |v20|
	v_add_f32_e64 v2, v2, |v22|
	v_add_f32_e64 v2, v2, |v24|
	v_add_f32_e64 v2, v2, |v26|
	v_add_f32_e64 v2, v2, |v28|
	v_add_f32_e64 v2, v2, |v30|
	s_waitcnt vmcnt(0)
	v_add_f32_e64 v4, v2, |v32|
	v_and_b32_e32 v2, 64, v213
	v_add_u32_e32 v12, 64, v2
	v_xor_b32_e32 v2, 32, v213
	v_cmp_lt_i32_e32 vcc, v2, v12
	v_mov_b32_e32 v20, v135
	ds_write_b64 v148, v[32:33] offset:61440
	v_cndmask_b32_e32 v2, v213, v2, vcc
	v_lshlrev_b32_e32 v2, 2, v2
	ds_bpermute_b32 v6, v2, v4
	s_waitcnt lgkmcnt(0)
	v_add_f32_e32 v6, v4, v6
	v_xor_b32_e32 v4, 16, v213
	v_cmp_lt_i32_e32 vcc, v4, v12
	v_and_b32_e32 v20, 63, v20
	s_nop 0
	v_cndmask_b32_e32 v4, v213, v4, vcc
	v_lshlrev_b32_e32 v4, 2, v4
	ds_bpermute_b32 v8, v4, v6
	s_waitcnt lgkmcnt(0)
	v_add_f32_e32 v8, v6, v8
	v_xor_b32_e32 v6, 8, v213
	v_cmp_lt_i32_e32 vcc, v6, v12
	s_nop 1
	v_cndmask_b32_e32 v6, v213, v6, vcc
	v_lshlrev_b32_e32 v6, 2, v6
	ds_bpermute_b32 v10, v6, v8
	s_waitcnt lgkmcnt(0)
	v_add_f32_e32 v10, v8, v10
	v_xor_b32_e32 v8, 4, v213
	v_cmp_lt_i32_e32 vcc, v8, v12
	s_nop 1
	v_cndmask_b32_e32 v8, v213, v8, vcc
	v_lshlrev_b32_e32 v8, 2, v8
	ds_bpermute_b32 v14, v8, v10
	s_waitcnt lgkmcnt(0)
	v_add_f32_e32 v16, v10, v14
	v_xor_b32_e32 v10, 2, v213
	v_cmp_lt_i32_e32 vcc, v10, v12
	v_mov_b32_e32 v14, v135
	s_nop 0
	v_cndmask_b32_e32 v10, v213, v10, vcc
	v_lshlrev_b32_e32 v10, 2, v10
	ds_bpermute_b32 v18, v10, v16
	s_barrier
	s_waitcnt lgkmcnt(0)
	v_add_f32_e32 v16, v16, v18
	v_xor_b32_e32 v18, 1, v213
	v_cmp_lt_i32_e32 vcc, v18, v12
	s_nop 1
	v_cndmask_b32_e32 v12, v213, v18, vcc
	v_lshlrev_b32_e32 v12, 2, v12
	ds_bpermute_b32 v18, v12, v16
	v_cmp_eq_u32_e32 vcc, 0, v20
	s_and_saveexec_b64 s[0:1], vcc
	s_xor_b64 s[0:1], exec, s[0:1]
	s_cbranch_execz .LBB0_817
	v_ashrrev_i32_e32 v14, 6, v14
	s_waitcnt lgkmcnt(0)
	v_add_f32_e32 v16, v16, v18
	v_lshlrev_b32_e32 v14, 2, v14
	ds_write_b32 v14, v16 offset:32
